# Res GEMM (down/out-proj) unit order reversed: L = nwg-1-L so the most recently written mid/hb rows are read first
# speedup vs baseline: 1.0029x; 1.0029x over previous
;     __host__ __device__ bool next(int i, Unit& u) const {
;         const long L = (long)i * G + c; if (L >= nwg) return false;
;         int wgid = (int)L; { const int q = nwg / NXCD, r = nwg % NXCD, xcd = wgid % NXCD, off = wgid / NXCD; wgid = (xcd < r ? xcd * (q + 1) : r * (q + 1) + (xcd - r) * q) + off; }
;         const int nig = WGM * nN, gid = wgid / nig, fm = gid * WGM, gsz = (nM - fm) < WGM ? (nM - fm) : WGM;
;         u.pm = fm + ((wgid % nig) % gsz); u.pn = (wgid % nig) / gsz; return true;
.LBB0_661:
	s_lshr_b32 s1, s17, 6
	v_mbcnt_lo_u32_b32 v0, -1, 0
	v_mbcnt_hi_u32_b32 v0, -1, v0
	s_cmpk_lt_i32 s85, 0x400
	s_waitcnt vmcnt(0)
	v_add_u32_e32 v18, s3, v0
	s_cselect_b64 s[28:29], -1, 0
	v_readfirstlane_b32 s22, v18
	s_cmpk_gt_i32 s85, 0x3ff
	s_cbranch_scc1 .LBB0_667
	s_sub_i32 s23, 0x3ff, s85
	s_ashr_i32 s2, s23, 31
	s_lshr_b32 s2, s2, 29
	s_add_i32 s2, s23, s2
	s_and_b32 s4, s2, -8
	s_sub_i32 s4, s23, s4
	s_cmp_gt_i32 s4, -1
	s_mov_b64 s[36:37], -1
	s_cbranch_scc0 .LBB0_664
	s_lshl_b32 s18, s4, 7
	s_mov_b64 s[36:37], 0

;     __host__ __device__ bool next(int i, Unit& u) const {
;         const long L = (long)i * G + c; if (L >= nwg) return false;
;         int wgid = (int)L; { const int q = nwg / NXCD, r = nwg % NXCD, xcd = wgid % NXCD, off = wgid / NXCD; wgid = (xcd < r ? xcd * (q + 1) : r * (q + 1) + (xcd - r) * q) + off; }
;         const int nig = WGM * nN, gid = wgid / nig, fm = gid * WGM, gsz = (nM - fm) < WGM ? (nM - fm) : WGM;
;         u.pm = fm + ((wgid % nig) % gsz); u.pn = (wgid % nig) / gsz; return true;
; template <class Epi>
; __device__ __forceinline__ void gemm_phase(LAS unsigned char* lds, const Gemm g, const StaticOrder& S, const Epi& E, int tid_) {
;     ...
;         const bool has_next = S.next(ui + 1, nxt);
.LBB0_673:
	s_add_i32 s62, s62, 1
	s_mul_i32 s22, s62, s65
	s_mul_hi_u32 s23, s62, s0
	s_add_i32 s23, s23, s22
	s_mul_i32 s22, s62, s0
	s_add_u32 s38, s22, s85
	s_addc_u32 s39, s23, s66
	v_cmp_gt_i64_e32 vcc, s[38:39], v[196:197]
	v_cmp_lt_i64_e64 s[40:41], s[38:39], v[194:195]
	s_cbranch_vccnz .LBB0_679
	s_sub_i32 s38, 0x3ff, s38
	s_ashr_i32 s22, s38, 31
	s_lshr_b32 s22, s22, 29
	s_add_i32 s22, s38, s22
	s_and_b32 s23, s22, -8
	s_sub_i32 s23, s38, s23
	s_cmp_gt_i32 s23, -1
	s_mov_b64 s[38:39], -1
	s_cbranch_scc0 .LBB0_676
	s_lshl_b32 s52, s23, 7
	s_mov_b64 s[38:39], 0
